# v35 + LN1: all eight gamma/beta LDS reads of a token issued together near the top of the iteration (the chunk 1-3 reads were issued right before use)
# baseline (speedup 1.0000x reference)
.LBB0_552:
	s_add_i32 s23, s7, 1
	s_waitcnt vmcnt(0)
	v_mov_b64_e32 v[38:39], v[84:85]
	v_mov_b64_e32 v[32:33], v[92:93]
	v_mov_b64_e32 v[34:35], v[90:91]
	v_mov_b64_e32 v[36:37], v[88:89]
	v_mov_b32_e32 v0, s23
	v_min_u32_e32 v0, 15, v0
	v_mov_b32_e32 v1, 0
	v_lshl_add_u64 v[0:1], v[82:83], 0, v[0:1]
	v_lshlrev_b64 v[2:3], 12, v[0:1]
	v_lshlrev_b64 v[0:1], 11, v[0:1]
	v_lshl_add_u64 v[12:13], v[62:63], 0, v[2:3]
	v_lshl_add_u64 v[92:93], v[64:65], 0, v[0:1]
	global_load_dwordx4 v[0:3], v[12:13], off nt
	global_load_dwordx2 v[84:85], v[92:93], off nt
	global_load_dwordx4 v[4:7], v[12:13], off offset:1024 nt
	global_load_dwordx2 v[88:89], v[92:93], off offset:512 nt
	global_load_dwordx4 v[8:11], v[12:13], off offset:2048 nt
	global_load_dwordx2 v[90:91], v[92:93], off offset:1024 nt
	s_nop 0
	global_load_dwordx4 v[12:15], v[12:13], off offset:3072 nt
	s_nop 0
	global_load_dwordx2 v[92:93], v[92:93], off offset:1536 nt
	v_lshlrev_b32_e32 v40, 16, v38
	v_and_b32_e32 v41, 0xffff0000, v38
	v_lshlrev_b32_e32 v38, 16, v39
	v_and_b32_e32 v39, 0xffff0000, v39
	v_lshlrev_b32_e32 v54, 16, v36
	v_and_b32_e32 v55, 0xffff0000, v36
	v_lshlrev_b32_e32 v94, 16, v37
	v_and_b32_e32 v95, 0xffff0000, v37
	v_lshlrev_b32_e32 v96, 16, v34
	v_and_b32_e32 v97, 0xffff0000, v34
	v_lshlrev_b32_e32 v100, 16, v35
	v_and_b32_e32 v101, 0xffff0000, v35
	v_lshlrev_b32_e32 v102, 16, v32
	v_and_b32_e32 v103, 0xffff0000, v32
	v_lshlrev_b32_e32 v104, 16, v33
	v_and_b32_e32 v105, 0xffff0000, v33
	v_pk_fma_f32 v[106:107], v[30:31], s[22:23], v[38:39] op_sel_hi:[1,0,1]
	ds_read_b128 v[30:33], v234
	ds_read_b128 v[34:37], v234 offset:4096
	ds_read_b128 v[130:133], v234 offset:1024
	ds_read_b128 v[134:137], v234 offset:5120
	ds_read_b128 v[138:141], v234 offset:2048
	ds_read_b128 v[142:145], v234 offset:6144
	ds_read_b128 v[146:149], v234 offset:3072
	ds_read_b128 v[150:153], v234 offset:7168
	v_pk_fma_f32 v[28:29], v[28:29], s[22:23], v[40:41] op_sel_hi:[1,0,1]
	v_pk_fma_f32 v[20:21], v[20:21], s[22:23], v[54:55] op_sel_hi:[1,0,1]
	v_add_f32_e32 v38, v28, v29
	v_add_f32_e32 v38, v38, v106
	v_pk_fma_f32 v[22:23], v[22:23], s[22:23], v[94:95] op_sel_hi:[1,0,1]
	v_add_f32_e32 v54, v20, v21
	v_pk_fma_f32 v[24:25], v[24:25], s[22:23], v[96:97] op_sel_hi:[1,0,1]
	v_add_f32_e32 v38, v107, v38
	v_add_f32_e32 v54, v54, v22
	v_pk_fma_f32 v[26:27], v[26:27], s[22:23], v[100:101] op_sel_hi:[1,0,1]
	v_add_f32_e32 v55, v24, v25
	v_add_f32_e32 v98, 0, v38
	v_add_f32_e32 v54, v23, v54
	v_add_f32_e32 v55, v55, v26
	v_add_f32_e32 v54, v98, v54
	v_add_f32_e32 v55, v27, v55
	v_pk_fma_f32 v[16:17], v[16:17], s[22:23], v[102:103] op_sel_hi:[1,0,1]
	v_add_f32_e32 v54, v54, v55
	v_pk_fma_f32 v[18:19], v[18:19], s[22:23], v[104:105] op_sel_hi:[1,0,1]
	v_add_f32_e32 v55, v16, v17
	v_add_f32_e32 v55, v55, v18
	v_add_f32_e32 v55, v19, v55
	v_add_f32_e32 v54, v54, v55
	s_nop 1
	v_add_f32_dpp v54, v54, v54 quad_perm:[1,0,3,2] row_mask:0xf bank_mask:0xf bound_ctrl:1
	s_nop 1
	v_add_f32_dpp v54, v54, v54 quad_perm:[2,3,0,1] row_mask:0xf bank_mask:0xf bound_ctrl:1
	s_nop 1
	v_add_f32_dpp v54, v54, v54 row_half_mirror row_mask:0xf bank_mask:0xf bound_ctrl:1
	s_nop 1
	v_add_f32_dpp v54, v54, v54 row_mirror row_mask:0xf bank_mask:0xf bound_ctrl:1
	s_nop 0
	v_readlane_b32 s2, v54, 16
	v_readlane_b32 s4, v54, 48
	v_readlane_b32 s0, v54, 0
	v_readlane_b32 s1, v54, 32
	v_mov_b32_e32 v54, s2
	v_mov_b32_e32 v55, s4
	v_pk_add_f32 v[54:55], s[0:1], v[54:55]
	s_nop 0
	v_add_f32_e32 v54, v54, v55
	v_mul_f32_e32 v54, 0x3a800000, v54
	v_pk_add_f32 v[28:29], v[28:29], v[54:55] op_sel_hi:[1,0] neg_lo:[0,1] neg_hi:[0,1]
	v_pk_add_f32 v[126:127], v[106:107], v[54:55] op_sel_hi:[1,0] neg_lo:[0,1] neg_hi:[0,1]
	v_pk_mul_f32 v[104:105], v[28:29], v[28:29]
	v_pk_mul_f32 v[106:107], v[126:127], v[126:127]
	v_pk_add_f32 v[158:159], v[20:21], v[54:55] op_sel_hi:[1,0] neg_lo:[0,1] neg_hi:[0,1]
	v_pk_add_f32 v[160:161], v[22:23], v[54:55] op_sel_hi:[1,0] neg_lo:[0,1] neg_hi:[0,1]
	v_pk_add_f32 v[100:101], v[24:25], v[54:55] op_sel_hi:[1,0] neg_lo:[0,1] neg_hi:[0,1]
	v_pk_add_f32 v[102:103], v[26:27], v[54:55] op_sel_hi:[1,0] neg_lo:[0,1] neg_hi:[0,1]
	v_pk_add_f32 v[94:95], v[16:17], v[54:55] op_sel_hi:[1,0] neg_lo:[0,1] neg_hi:[0,1]
	v_pk_add_f32 v[96:97], v[18:19], v[54:55] op_sel_hi:[1,0] neg_lo:[0,1] neg_hi:[0,1]
	v_add_f32_e32 v54, v104, v105
	v_add_f32_e32 v54, v106, v54
	v_pk_mul_f32 v[20:21], v[158:159], v[158:159]
	v_add_f32_e32 v54, v107, v54
	v_add_f32_e32 v20, v20, v54
	v_pk_mul_f32 v[22:23], v[160:161], v[160:161]
	v_add_f32_e32 v20, v21, v20
	v_add_f32_e32 v20, v22, v20
	v_pk_mul_f32 v[24:25], v[100:101], v[100:101]
	v_add_f32_e32 v20, v23, v20
	v_add_f32_e32 v20, v24, v20
	v_pk_mul_f32 v[26:27], v[102:103], v[102:103]
	v_add_f32_e32 v20, v25, v20
	v_add_f32_e32 v20, v26, v20
	v_pk_mul_f32 v[16:17], v[94:95], v[94:95]
	v_add_f32_e32 v20, v27, v20
	v_add_f32_e32 v16, v16, v20
	v_pk_mul_f32 v[18:19], v[96:97], v[96:97]
	v_add_f32_e32 v16, v17, v16
	v_add_f32_e32 v16, v18, v16
	v_add_f32_e32 v16, v19, v16
	s_nop 1
	v_add_f32_dpp v16, v16, v16 quad_perm:[1,0,3,2] row_mask:0xf bank_mask:0xf bound_ctrl:1
	s_nop 1
	v_add_f32_dpp v16, v16, v16 quad_perm:[2,3,0,1] row_mask:0xf bank_mask:0xf bound_ctrl:1
	s_nop 1
	v_add_f32_dpp v16, v16, v16 row_half_mirror row_mask:0xf bank_mask:0xf bound_ctrl:1
	s_nop 1
	v_add_f32_dpp v16, v16, v16 row_mirror row_mask:0xf bank_mask:0xf bound_ctrl:1
	s_nop 0
	v_readlane_b32 s2, v16, 16
	v_readlane_b32 s4, v16, 48
	v_readlane_b32 s0, v16, 0
	v_readlane_b32 s1, v16, 32
	v_mov_b32_e32 v16, s2
	v_mov_b32_e32 v17, s4
	v_pk_add_f32 v[16:17], s[0:1], v[16:17]
	s_mov_b32 s0, 0x800000
	v_add_f32_e32 v16, v16, v17
	v_fmamk_f32 v16, v16, 0x3a800000, v116
	v_cmp_gt_f32_e32 vcc, s0, v16
	v_mul_f32_e32 v17, 0x4b800000, v16
	s_nop 0
	v_cndmask_b32_e32 v16, v16, v17, vcc
	v_rsq_f32_e32 v54, v16
	s_nop 0
	v_mul_f32_e32 v55, 0x45800000, v54
	v_cndmask_b32_e32 v98, v54, v55, vcc
	v_pk_mul_f32 v[28:29], v[28:29], v[98:99] op_sel_hi:[1,0]
	s_waitcnt lgkmcnt(6)
	v_pk_fma_f32 v[106:107], v[30:31], v[28:29], v[34:35]
	v_pk_mul_f32 v[28:29], v[126:127], v[98:99] op_sel_hi:[1,0]
	v_pk_fma_f32 v[104:105], v[32:33], v[28:29], v[36:37]
	v_cvt_pk_bf16_f32 v28, v106, v107
	v_cvt_pk_bf16_f32 v29, v104, v105
	v_mul_f32_e32 v252, v106, v183
	v_mul_f32_e32 v253, v106, v184
	v_mul_f32_e32 v254, v106, v182
	v_mul_f32_e32 v255, v106, v185
	v_fmac_f32_e32 v252, v107, v187
	v_fmac_f32_e32 v253, v107, v188
	v_fmac_f32_e32 v254, v107, v186
	v_fmac_f32_e32 v255, v107, v189
	v_fmac_f32_e32 v252, v104, v191
	v_fmac_f32_e32 v253, v104, v192
	v_fmac_f32_e32 v254, v104, v190
	v_fmac_f32_e32 v255, v104, v193
	v_fmac_f32_e32 v252, v105, v195
	v_fmac_f32_e32 v253, v105, v196
	v_fmac_f32_e32 v254, v105, v194
	v_fmac_f32_e32 v255, v105, v197
	global_store_dwordx2 v[86:87], v[28:29], off offset:-1024
	v_pk_mul_f32 v[40:41], v[158:159], v[98:99] op_sel_hi:[1, 0]
	s_waitcnt lgkmcnt(4)
	v_pk_fma_f32 v[108:109], v[40:41], v[130:131], v[134:135]
	v_pk_mul_f32 v[32:33], v[160:161], v[98:99] op_sel_hi:[1, 0]
	v_pk_fma_f32 v[110:111], v[32:33], v[132:133], v[136:137]
	v_cvt_pk_bf16_f32 v32, v108, v109
	v_cvt_pk_bf16_f32 v33, v110, v111
	v_fmac_f32_e32 v252, v108, v199
	v_fmac_f32_e32 v253, v108, v200
	v_fmac_f32_e32 v254, v108, v198
	v_fmac_f32_e32 v255, v108, v201
	v_fmac_f32_e32 v252, v109, v203
	v_fmac_f32_e32 v253, v109, v204
	v_fmac_f32_e32 v254, v109, v202
	v_fmac_f32_e32 v255, v109, v205
	v_fmac_f32_e32 v252, v110, v207
	v_fmac_f32_e32 v253, v110, v208
	v_fmac_f32_e32 v254, v110, v206
	v_fmac_f32_e32 v255, v110, v209
	v_fmac_f32_e32 v252, v111, v211
	v_fmac_f32_e32 v253, v111, v212
	v_fmac_f32_e32 v254, v111, v210
	v_fmac_f32_e32 v255, v111, v213
	global_store_dwordx2 v[86:87], v[32:33], off offset:-512
	v_pk_mul_f32 v[20:21], v[102:103], v[98:99] op_sel_hi:[1, 0]
	s_waitcnt lgkmcnt(2)
	v_pk_fma_f32 v[50:51], v[20:21], v[140:141], v[144:145]
	v_pk_mul_f32 v[16:17], v[100:101], v[98:99] op_sel_hi:[1, 0]
	v_cvt_pk_bf16_f32 v21, v50, v51
	v_pk_fma_f32 v[48:49], v[16:17], v[138:139], v[142:143]
	v_cvt_pk_bf16_f32 v20, v48, v49
	v_fmac_f32_e32 v252, v50, v223
	v_fmac_f32_e32 v253, v50, v224
	v_fmac_f32_e32 v254, v50, v222
	v_fmac_f32_e32 v255, v50, v225
	v_fmac_f32_e32 v252, v51, v227
	v_fmac_f32_e32 v253, v51, v228
	v_fmac_f32_e32 v254, v51, v226
	v_fmac_f32_e32 v255, v51, v229
	v_fmac_f32_e32 v252, v48, v215
	v_fmac_f32_e32 v253, v48, v216
	v_fmac_f32_e32 v254, v48, v214
	v_fmac_f32_e32 v255, v48, v217
	v_fmac_f32_e32 v252, v49, v219
	v_fmac_f32_e32 v253, v49, v220
	v_fmac_f32_e32 v254, v49, v218
	v_fmac_f32_e32 v255, v49, v221
	global_store_dwordx2 v[86:87], v[20:21], off
	v_pk_mul_f32 v[46:47], v[94:95], v[98:99] op_sel_hi:[1, 0]
	s_waitcnt lgkmcnt(0)
	v_pk_fma_f32 v[52:53], v[46:47], v[146:147], v[150:151]
	v_pk_mul_f32 v[32:33], v[96:97], v[98:99] op_sel_hi:[1, 0]
	v_pk_fma_f32 v[54:55], v[32:33], v[148:149], v[152:153]
	v_cvt_pk_bf16_f32 v32, v52, v53
	v_cvt_pk_bf16_f32 v33, v54, v55
	v_fmac_f32_e32 v252, v52, v231
	v_fmac_f32_e32 v253, v52, v232
	v_fmac_f32_e32 v254, v52, v230
	v_fmac_f32_e32 v255, v52, v233
	v_fmac_f32_e32 v252, v53, v239
	v_fmac_f32_e32 v253, v53, v240
	v_fmac_f32_e32 v254, v53, v238
	v_fmac_f32_e32 v255, v53, v241
	v_fmac_f32_e32 v252, v54, v243
	v_fmac_f32_e32 v253, v54, v244
	v_fmac_f32_e32 v254, v54, v242
	v_fmac_f32_e32 v255, v54, v245
	v_fmac_f32_e32 v252, v55, v247
	v_fmac_f32_e32 v253, v55, v248
	v_fmac_f32_e32 v254, v55, v246
	v_fmac_f32_e32 v255, v55, v249
	global_store_dwordx2 v[86:87], v[32:33], off offset:512
	v_add_f32_dpp v250, v252, v252 row_mirror row_mask:0xf bank_mask:0xf bound_ctrl:1
	v_add_f32_dpp v250, v253, v253 row_mirror row_mask:0xf bank_mask:0xc bound_ctrl:1
	v_add_f32_dpp v251, v254, v254 row_mirror row_mask:0xf bank_mask:0xf bound_ctrl:1
	v_add_f32_dpp v251, v255, v255 row_mirror row_mask:0xf bank_mask:0xc bound_ctrl:1
	v_add_f32_dpp v250, v250, v250 row_half_mirror row_mask:0xf bank_mask:0xf bound_ctrl:1
	s_nop 0
	v_add_f32_dpp v250, v251, v251 row_half_mirror row_mask:0xf bank_mask:0xa bound_ctrl:1
	s_nop 1
	v_add_f32_dpp v250, v250, v250 quad_perm:[1, 0, 3, 2] row_mask:0xf bank_mask:0xf bound_ctrl:1
	s_nop 1
	v_add_f32_dpp v250, v250, v250 quad_perm:[2, 3, 0, 1] row_mask:0xf bank_mask:0xf bound_ctrl:1
	s_nop 0
	v_readlane_b32 s2, v250, 20
	v_readlane_b32 s4, v250, 52
	v_readlane_b32 s0, v250, 4
	v_readlane_b32 s1, v250, 36
	v_mov_b32_e32 v16, s2
	v_mov_b32_e32 v17, s4
	v_readlane_b32 s2, v250, 16
	v_readlane_b32 s4, v250, 48
	v_pk_add_f32 v[16:17], s[0:1], v[16:17]
	v_readlane_b32 s0, v250, 0
	v_readlane_b32 s1, v250, 32
	v_mov_b32_e32 v18, s2
	v_mov_b32_e32 v19, s4
	v_readlane_b32 s2, v250, 24
	v_readlane_b32 s4, v250, 56
	v_pk_add_f32 v[18:19], s[0:1], v[18:19]
	v_readlane_b32 s0, v250, 8
	v_readlane_b32 s1, v250, 40
	v_mov_b32_e32 v20, s2
	v_mov_b32_e32 v21, s4
	v_pk_add_f32 v[20:21], s[0:1], v[20:21]
	v_mov_b32_e32 v25, v18
	v_add_f32_e32 v26, v20, v21
	v_mov_b32_e32 v18, v17
	v_readlane_b32 s2, v250, 28
	v_readlane_b32 s4, v250, 60
	v_readlane_b32 s0, v250, 12
	v_readlane_b32 s1, v250, 44
	v_mov_b32_e32 v20, s2
	v_mov_b32_e32 v21, s4
	v_pk_add_f32 v[20:21], s[0:1], v[20:21]
	v_add_f32_e32 v27, v20, v21
	v_mov_b32_e32 v24, v16
	v_pk_add_f32 v[16:17], v[24:25], v[18:19]
	v_mov_b32_e32 v20, v178
	v_mov_b32_e32 v21, v179
	v_mov_b32_e32 v22, v180
	v_mov_b32_e32 v23, v181
	v_add_f32_e32 v19, v26, v22
	v_pk_add_f32 v[16:17], v[16:17], v[20:21]
	v_add_f32_e32 v18, v27, v23
	v_cmp_gt_f32_e32 vcc, v17, v16
	s_nop 0
	s_nop 0
	v_cndmask_b32_e32 v20, v16, v17, vcc
	v_cmp_gt_f32_e64 s[18:19], v19, v20
	v_cndmask_b32_e64 v21, 0, 1, vcc
	s_and_b64 s[14:15], s[18:19], exec
	v_cndmask_b32_e64 v20, v20, v19, s[18:19]
	v_cmp_ngt_f32_e64 s[0:1], v18, v20
	v_readfirstlane_b32 s2, v21
	s_cselect_b32 s2, 2, s2
	s_and_b64 s[14:15], s[0:1], exec
	s_cselect_b32 s2, s2, 3
	s_cmp_eq_u32 s2, 0
	s_waitcnt lgkmcnt(0)
	s_cbranch_scc0 .Lmy_rsela_1
	ds_read_b128 v[146:149], v60
	ds_read_b128 v[150:153], v60 offset:4096
	ds_read_b128 v[154:157], v60 offset:8192
	ds_read_b128 v[66:69], v60 offset:12288
	ds_read_b128 v[130:133], v60 offset:1024
	ds_read_b128 v[134:137], v60 offset:5120
	ds_read_b128 v[138:141], v60 offset:9216
	ds_read_b128 v[142:145], v60 offset:13312
	s_waitcnt lgkmcnt(7)
	v_mul_f32_e32 v252, v106, v146
	v_fmac_f32_e32 v252, v107, v147
	v_fmac_f32_e32 v252, v104, v148
	v_fmac_f32_e32 v252, v105, v149
	s_waitcnt lgkmcnt(6)
	v_mul_f32_e32 v253, v106, v150
	v_fmac_f32_e32 v253, v107, v151
	v_fmac_f32_e32 v253, v104, v152
	v_fmac_f32_e32 v253, v105, v153
	s_waitcnt lgkmcnt(5)
	v_mul_f32_e32 v254, v106, v154
	v_fmac_f32_e32 v254, v107, v155
	v_fmac_f32_e32 v254, v104, v156
	v_fmac_f32_e32 v254, v105, v157
	s_waitcnt lgkmcnt(4)
	v_mul_f32_e32 v255, v106, v66
	v_fmac_f32_e32 v255, v107, v67
	v_fmac_f32_e32 v255, v104, v68
	v_fmac_f32_e32 v255, v105, v69
	ds_read_b128 v[146:149], v60 offset:2048
	ds_read_b128 v[150:153], v60 offset:6144
	ds_read_b128 v[154:157], v60 offset:10240
	ds_read_b128 v[66:69], v60 offset:14336
	s_waitcnt lgkmcnt(7)
	v_fmac_f32_e32 v252, v108, v130
	v_fmac_f32_e32 v252, v109, v131
	v_fmac_f32_e32 v252, v110, v132
	v_fmac_f32_e32 v252, v111, v133
	s_waitcnt lgkmcnt(6)
	v_fmac_f32_e32 v253, v108, v134
	v_fmac_f32_e32 v253, v109, v135
	v_fmac_f32_e32 v253, v110, v136
	v_fmac_f32_e32 v253, v111, v137
	s_waitcnt lgkmcnt(5)
	v_fmac_f32_e32 v254, v108, v138
	v_fmac_f32_e32 v254, v109, v139
	v_fmac_f32_e32 v254, v110, v140
	v_fmac_f32_e32 v254, v111, v141
	s_waitcnt lgkmcnt(4)
	v_fmac_f32_e32 v255, v108, v142
	v_fmac_f32_e32 v255, v109, v143
	v_fmac_f32_e32 v255, v110, v144
	v_fmac_f32_e32 v255, v111, v145
	ds_read_b128 v[130:133], v60 offset:3072
	ds_read_b128 v[134:137], v60 offset:7168
	ds_read_b128 v[138:141], v60 offset:11264
	ds_read_b128 v[142:145], v60 offset:15360
	s_waitcnt lgkmcnt(7)
	v_fmac_f32_e32 v252, v50, v148
	v_fmac_f32_e32 v252, v51, v149
	v_fmac_f32_e32 v252, v48, v146
	v_fmac_f32_e32 v252, v49, v147
	s_waitcnt lgkmcnt(6)
	v_fmac_f32_e32 v253, v50, v152
	v_fmac_f32_e32 v253, v51, v153
	v_fmac_f32_e32 v253, v48, v150
	v_fmac_f32_e32 v253, v49, v151
	s_waitcnt lgkmcnt(5)
	v_fmac_f32_e32 v254, v50, v156
	v_fmac_f32_e32 v254, v51, v157
	v_fmac_f32_e32 v254, v48, v154
	v_fmac_f32_e32 v254, v49, v155
	s_waitcnt lgkmcnt(4)
	v_fmac_f32_e32 v255, v50, v68
	v_fmac_f32_e32 v255, v51, v69
	v_fmac_f32_e32 v255, v48, v66
	v_fmac_f32_e32 v255, v49, v67
	s_waitcnt lgkmcnt(3)
	v_fmac_f32_e32 v252, v52, v130
	v_fmac_f32_e32 v252, v53, v131
	v_fmac_f32_e32 v252, v54, v132
	v_fmac_f32_e32 v252, v55, v133
	s_waitcnt lgkmcnt(2)
	v_fmac_f32_e32 v253, v52, v134
	v_fmac_f32_e32 v253, v53, v135
	v_fmac_f32_e32 v253, v54, v136
	v_fmac_f32_e32 v253, v55, v137
	s_waitcnt lgkmcnt(1)
	v_fmac_f32_e32 v254, v52, v138
	v_fmac_f32_e32 v254, v53, v139
	v_fmac_f32_e32 v254, v54, v140
	v_fmac_f32_e32 v254, v55, v141
	s_waitcnt lgkmcnt(0)
	v_fmac_f32_e32 v255, v52, v142
	v_fmac_f32_e32 v255, v53, v143
	v_fmac_f32_e32 v255, v54, v144
	v_fmac_f32_e32 v255, v55, v145
	v_add_f32_dpp v94, v252, v252 row_mirror row_mask:0xf bank_mask:0xf bound_ctrl:1
	v_add_f32_dpp v94, v253, v253 row_mirror row_mask:0xf bank_mask:0xc bound_ctrl:1
	v_add_f32_dpp v96, v254, v254 row_mirror row_mask:0xf bank_mask:0xf bound_ctrl:1
	v_add_f32_dpp v96, v255, v255 row_mirror row_mask:0xf bank_mask:0xc bound_ctrl:1
	v_add_f32_dpp v94, v94, v94 row_half_mirror row_mask:0xf bank_mask:0xf bound_ctrl:1
	s_nop 0
	v_add_f32_dpp v94, v96, v96 row_half_mirror row_mask:0xf bank_mask:0xa bound_ctrl:1
	s_nop 1
	v_add_f32_dpp v94, v94, v94 quad_perm:[1,0,3,2] row_mask:0xf bank_mask:0xf bound_ctrl:1
	s_nop 1
	v_add_f32_dpp v94, v94, v94 quad_perm:[2,3,0,1] row_mask:0xf bank_mask:0xf bound_ctrl:1
	s_nop 0
	v_readlane_b32 s20, v94, 0
	v_readlane_b32 s4, v94, 16
	v_readlane_b32 s21, v94, 32
	v_readlane_b32 s5, v94, 48
	v_readlane_b32 s91, v94, 8
	v_readlane_b32 s95, v94, 24
	v_readlane_b32 s94, v94, 40
	v_readlane_b32 s92, v94, 56
	v_readlane_b32 s6, v94, 4
	v_readlane_b32 s75, v94, 20
	v_readlane_b32 s74, v94, 36
	v_readlane_b32 s84, v94, 52
	v_readlane_b32 s97, v94, 12
	v_readlane_b32 s9, v94, 28
	v_readlane_b32 s8, v94, 44
	v_readlane_b32 s12, v94, 60
	s_branch .Lmy_rsela_end

.LBB0_1676:
	s_add_i32 s21, s19, 1
	s_waitcnt vmcnt(0)
	v_mov_b64_e32 v[38:39], v[84:85]
	v_mov_b64_e32 v[32:33], v[92:93]
	v_mov_b64_e32 v[34:35], v[90:91]
	v_mov_b64_e32 v[36:37], v[88:89]
	v_mov_b32_e32 v0, s21
	v_min_u32_e32 v0, 15, v0
	v_mov_b32_e32 v1, 0
	v_lshl_add_u64 v[0:1], v[82:83], 0, v[0:1]
	v_lshlrev_b64 v[2:3], 12, v[0:1]
	v_lshlrev_b64 v[0:1], 11, v[0:1]
	v_lshl_add_u64 v[12:13], v[62:63], 0, v[2:3]
	v_lshl_add_u64 v[92:93], v[64:65], 0, v[0:1]
	global_load_dwordx4 v[0:3], v[12:13], off nt
	global_load_dwordx2 v[84:85], v[92:93], off nt
	global_load_dwordx4 v[4:7], v[12:13], off offset:1024 nt
	global_load_dwordx2 v[88:89], v[92:93], off offset:512 nt
	global_load_dwordx4 v[8:11], v[12:13], off offset:2048 nt
	global_load_dwordx2 v[90:91], v[92:93], off offset:1024 nt
	s_nop 0
	global_load_dwordx4 v[12:15], v[12:13], off offset:3072 nt
	s_nop 0
	global_load_dwordx2 v[92:93], v[92:93], off offset:1536 nt
	v_lshlrev_b32_e32 v40, 16, v38
	v_and_b32_e32 v41, 0xffff0000, v38
	v_lshlrev_b32_e32 v38, 16, v39
	v_and_b32_e32 v39, 0xffff0000, v39
	v_lshlrev_b32_e32 v54, 16, v36
	v_and_b32_e32 v55, 0xffff0000, v36
	v_lshlrev_b32_e32 v94, 16, v37
	v_and_b32_e32 v95, 0xffff0000, v37
	v_lshlrev_b32_e32 v96, 16, v34
	v_and_b32_e32 v97, 0xffff0000, v34
	v_lshlrev_b32_e32 v100, 16, v35
	v_and_b32_e32 v101, 0xffff0000, v35
	v_lshlrev_b32_e32 v102, 16, v32
	v_and_b32_e32 v103, 0xffff0000, v32
	v_lshlrev_b32_e32 v104, 16, v33
	v_and_b32_e32 v105, 0xffff0000, v33
	v_pk_fma_f32 v[106:107], v[30:31], s[20:21], v[38:39] op_sel_hi:[1,0,1]
	ds_read_b128 v[30:33], v234
	ds_read_b128 v[34:37], v234 offset:4096
	ds_read_b128 v[130:133], v234 offset:1024
	ds_read_b128 v[134:137], v234 offset:5120
	ds_read_b128 v[138:141], v234 offset:2048
	ds_read_b128 v[142:145], v234 offset:6144
	ds_read_b128 v[146:149], v234 offset:3072
	ds_read_b128 v[150:153], v234 offset:7168
	v_pk_fma_f32 v[28:29], v[28:29], s[20:21], v[40:41] op_sel_hi:[1,0,1]
	v_pk_fma_f32 v[20:21], v[20:21], s[20:21], v[54:55] op_sel_hi:[1,0,1]
	v_add_f32_e32 v38, v28, v29
	v_add_f32_e32 v38, v38, v106
	v_pk_fma_f32 v[22:23], v[22:23], s[20:21], v[94:95] op_sel_hi:[1,0,1]
	v_add_f32_e32 v54, v20, v21
	v_pk_fma_f32 v[24:25], v[24:25], s[20:21], v[96:97] op_sel_hi:[1,0,1]
	v_add_f32_e32 v38, v107, v38
	v_add_f32_e32 v54, v54, v22
	v_pk_fma_f32 v[26:27], v[26:27], s[20:21], v[100:101] op_sel_hi:[1,0,1]
	v_add_f32_e32 v55, v24, v25
	v_add_f32_e32 v98, 0, v38
	v_add_f32_e32 v54, v23, v54
	v_add_f32_e32 v55, v55, v26
	v_add_f32_e32 v54, v98, v54
	v_add_f32_e32 v55, v27, v55
	v_pk_fma_f32 v[16:17], v[16:17], s[20:21], v[102:103] op_sel_hi:[1,0,1]
	v_add_f32_e32 v54, v54, v55
	v_pk_fma_f32 v[18:19], v[18:19], s[20:21], v[104:105] op_sel_hi:[1,0,1]
	v_add_f32_e32 v55, v16, v17
	v_add_f32_e32 v55, v55, v18
	v_add_f32_e32 v55, v19, v55
	v_add_f32_e32 v54, v54, v55
	s_nop 1
	v_add_f32_dpp v54, v54, v54 quad_perm:[1,0,3,2] row_mask:0xf bank_mask:0xf bound_ctrl:1
	s_nop 1
	v_add_f32_dpp v54, v54, v54 quad_perm:[2,3,0,1] row_mask:0xf bank_mask:0xf bound_ctrl:1
	s_nop 1
	v_add_f32_dpp v54, v54, v54 row_half_mirror row_mask:0xf bank_mask:0xf bound_ctrl:1
	s_nop 1
	v_add_f32_dpp v54, v54, v54 row_mirror row_mask:0xf bank_mask:0xf bound_ctrl:1
	s_nop 0
	v_readlane_b32 s2, v54, 16
	v_readlane_b32 s10, v54, 48
	v_readlane_b32 s0, v54, 0
	v_readlane_b32 s1, v54, 32
	v_mov_b32_e32 v54, s2
	v_mov_b32_e32 v55, s10
	v_pk_add_f32 v[54:55], s[0:1], v[54:55]
	s_nop 0
	v_add_f32_e32 v54, v54, v55
	v_mul_f32_e32 v54, 0x3a800000, v54
	v_pk_add_f32 v[28:29], v[28:29], v[54:55] op_sel_hi:[1,0] neg_lo:[0,1] neg_hi:[0,1]
	v_pk_add_f32 v[126:127], v[106:107], v[54:55] op_sel_hi:[1,0] neg_lo:[0,1] neg_hi:[0,1]
	v_pk_mul_f32 v[104:105], v[28:29], v[28:29]
	v_pk_mul_f32 v[106:107], v[126:127], v[126:127]
	v_pk_add_f32 v[158:159], v[20:21], v[54:55] op_sel_hi:[1,0] neg_lo:[0,1] neg_hi:[0,1]
	v_pk_add_f32 v[160:161], v[22:23], v[54:55] op_sel_hi:[1,0] neg_lo:[0,1] neg_hi:[0,1]
	v_pk_add_f32 v[100:101], v[24:25], v[54:55] op_sel_hi:[1,0] neg_lo:[0,1] neg_hi:[0,1]
	v_pk_add_f32 v[102:103], v[26:27], v[54:55] op_sel_hi:[1,0] neg_lo:[0,1] neg_hi:[0,1]
	v_pk_add_f32 v[94:95], v[16:17], v[54:55] op_sel_hi:[1,0] neg_lo:[0,1] neg_hi:[0,1]
	v_pk_add_f32 v[96:97], v[18:19], v[54:55] op_sel_hi:[1,0] neg_lo:[0,1] neg_hi:[0,1]
	v_add_f32_e32 v54, v104, v105
	v_add_f32_e32 v54, v106, v54
	v_pk_mul_f32 v[20:21], v[158:159], v[158:159]
	v_add_f32_e32 v54, v107, v54
	v_add_f32_e32 v20, v20, v54
	v_pk_mul_f32 v[22:23], v[160:161], v[160:161]
	v_add_f32_e32 v20, v21, v20
	v_add_f32_e32 v20, v22, v20
	v_pk_mul_f32 v[24:25], v[100:101], v[100:101]
	v_add_f32_e32 v20, v23, v20
	v_add_f32_e32 v20, v24, v20
	v_pk_mul_f32 v[26:27], v[102:103], v[102:103]
	v_add_f32_e32 v20, v25, v20
	v_add_f32_e32 v20, v26, v20
	v_pk_mul_f32 v[16:17], v[94:95], v[94:95]
	v_add_f32_e32 v20, v27, v20
	v_add_f32_e32 v16, v16, v20
	v_pk_mul_f32 v[18:19], v[96:97], v[96:97]
	v_add_f32_e32 v16, v17, v16
	v_add_f32_e32 v16, v18, v16
	v_add_f32_e32 v16, v19, v16
	s_nop 1
	v_add_f32_dpp v16, v16, v16 quad_perm:[1,0,3,2] row_mask:0xf bank_mask:0xf bound_ctrl:1
	s_nop 1
	v_add_f32_dpp v16, v16, v16 quad_perm:[2,3,0,1] row_mask:0xf bank_mask:0xf bound_ctrl:1
	s_nop 1
	v_add_f32_dpp v16, v16, v16 row_half_mirror row_mask:0xf bank_mask:0xf bound_ctrl:1
	s_nop 1
	v_add_f32_dpp v16, v16, v16 row_mirror row_mask:0xf bank_mask:0xf bound_ctrl:1
	s_nop 0
	v_readlane_b32 s2, v16, 16
	v_readlane_b32 s10, v16, 48
	v_readlane_b32 s0, v16, 0
	v_readlane_b32 s1, v16, 32
	v_mov_b32_e32 v16, s2
	v_mov_b32_e32 v17, s10
	v_pk_add_f32 v[16:17], s[0:1], v[16:17]
	s_mov_b32 s0, 0x800000
	v_add_f32_e32 v16, v16, v17
	v_fmamk_f32 v16, v16, 0x3a800000, v116
	v_cmp_gt_f32_e32 vcc, s0, v16
	v_mul_f32_e32 v17, 0x4b800000, v16
	s_nop 0
	v_cndmask_b32_e32 v16, v16, v17, vcc
	v_rsq_f32_e32 v54, v16
	s_nop 0
	v_mul_f32_e32 v55, 0x45800000, v54
	v_cndmask_b32_e32 v98, v54, v55, vcc
	v_pk_mul_f32 v[28:29], v[28:29], v[98:99] op_sel_hi:[1,0]
	s_waitcnt lgkmcnt(6)
	v_pk_fma_f32 v[106:107], v[30:31], v[28:29], v[34:35]
	v_pk_mul_f32 v[28:29], v[126:127], v[98:99] op_sel_hi:[1,0]
	v_pk_fma_f32 v[104:105], v[32:33], v[28:29], v[36:37]
	v_cvt_pk_bf16_f32 v28, v106, v107
	v_cvt_pk_bf16_f32 v29, v104, v105
	v_mul_f32_e32 v252, v106, v183
	v_mul_f32_e32 v253, v106, v184
	v_mul_f32_e32 v254, v106, v182
	v_mul_f32_e32 v255, v106, v185
	v_fmac_f32_e32 v252, v107, v187
	v_fmac_f32_e32 v253, v107, v188
	v_fmac_f32_e32 v254, v107, v186
	v_fmac_f32_e32 v255, v107, v189
	v_fmac_f32_e32 v252, v104, v191
	v_fmac_f32_e32 v253, v104, v192
	v_fmac_f32_e32 v254, v104, v190
	v_fmac_f32_e32 v255, v104, v193
	v_fmac_f32_e32 v252, v105, v195
	v_fmac_f32_e32 v253, v105, v196
	v_fmac_f32_e32 v254, v105, v194
	v_fmac_f32_e32 v255, v105, v197
	global_store_dwordx2 v[86:87], v[28:29], off offset:-1024
	v_pk_mul_f32 v[40:41], v[158:159], v[98:99] op_sel_hi:[1, 0]
	s_waitcnt lgkmcnt(4)
	v_pk_fma_f32 v[108:109], v[40:41], v[130:131], v[134:135]
	v_pk_mul_f32 v[32:33], v[160:161], v[98:99] op_sel_hi:[1, 0]
	v_pk_fma_f32 v[110:111], v[32:33], v[132:133], v[136:137]
	v_cvt_pk_bf16_f32 v32, v108, v109
	v_cvt_pk_bf16_f32 v33, v110, v111
	v_fmac_f32_e32 v252, v108, v199
	v_fmac_f32_e32 v253, v108, v200
	v_fmac_f32_e32 v254, v108, v198
	v_fmac_f32_e32 v255, v108, v201
	v_fmac_f32_e32 v252, v109, v203
	v_fmac_f32_e32 v253, v109, v204
	v_fmac_f32_e32 v254, v109, v202
	v_fmac_f32_e32 v255, v109, v205
	v_fmac_f32_e32 v252, v110, v207
	v_fmac_f32_e32 v253, v110, v208
	v_fmac_f32_e32 v254, v110, v206
	v_fmac_f32_e32 v255, v110, v209
	v_fmac_f32_e32 v252, v111, v211
	v_fmac_f32_e32 v253, v111, v212
	v_fmac_f32_e32 v254, v111, v210
	v_fmac_f32_e32 v255, v111, v213
	global_store_dwordx2 v[86:87], v[32:33], off offset:-512
	v_pk_mul_f32 v[20:21], v[102:103], v[98:99] op_sel_hi:[1, 0]
	s_waitcnt lgkmcnt(2)
	v_pk_fma_f32 v[50:51], v[20:21], v[140:141], v[144:145]
	v_pk_mul_f32 v[16:17], v[100:101], v[98:99] op_sel_hi:[1, 0]
	v_cvt_pk_bf16_f32 v21, v50, v51
	v_pk_fma_f32 v[48:49], v[16:17], v[138:139], v[142:143]
	v_cvt_pk_bf16_f32 v20, v48, v49
	v_fmac_f32_e32 v252, v50, v223
	v_fmac_f32_e32 v253, v50, v224
	v_fmac_f32_e32 v254, v50, v222
	v_fmac_f32_e32 v255, v50, v225
	v_fmac_f32_e32 v252, v51, v227
	v_fmac_f32_e32 v253, v51, v228
	v_fmac_f32_e32 v254, v51, v226
	v_fmac_f32_e32 v255, v51, v229
	v_fmac_f32_e32 v252, v48, v215
	v_fmac_f32_e32 v253, v48, v216
	v_fmac_f32_e32 v254, v48, v214
	v_fmac_f32_e32 v255, v48, v217
	v_fmac_f32_e32 v252, v49, v219
	v_fmac_f32_e32 v253, v49, v220
	v_fmac_f32_e32 v254, v49, v218
	v_fmac_f32_e32 v255, v49, v221
	global_store_dwordx2 v[86:87], v[20:21], off
	v_pk_mul_f32 v[46:47], v[94:95], v[98:99] op_sel_hi:[1, 0]
	s_waitcnt lgkmcnt(0)
	v_pk_fma_f32 v[52:53], v[46:47], v[146:147], v[150:151]
	v_pk_mul_f32 v[32:33], v[96:97], v[98:99] op_sel_hi:[1, 0]
	v_pk_fma_f32 v[54:55], v[32:33], v[148:149], v[152:153]
	v_cvt_pk_bf16_f32 v32, v52, v53
	v_cvt_pk_bf16_f32 v33, v54, v55
	v_fmac_f32_e32 v252, v52, v231
	v_fmac_f32_e32 v253, v52, v232
	v_fmac_f32_e32 v254, v52, v230
	v_fmac_f32_e32 v255, v52, v233
	v_fmac_f32_e32 v252, v53, v239
	v_fmac_f32_e32 v253, v53, v240
	v_fmac_f32_e32 v254, v53, v238
	v_fmac_f32_e32 v255, v53, v241
	v_fmac_f32_e32 v252, v54, v243
	v_fmac_f32_e32 v253, v54, v244
	v_fmac_f32_e32 v254, v54, v242
	v_fmac_f32_e32 v255, v54, v245
	v_fmac_f32_e32 v252, v55, v247
	v_fmac_f32_e32 v253, v55, v248
	v_fmac_f32_e32 v254, v55, v246
	v_fmac_f32_e32 v255, v55, v249
	global_store_dwordx2 v[86:87], v[32:33], off offset:512
	v_add_f32_dpp v250, v252, v252 row_mirror row_mask:0xf bank_mask:0xf bound_ctrl:1
	v_add_f32_dpp v250, v253, v253 row_mirror row_mask:0xf bank_mask:0xc bound_ctrl:1
	v_add_f32_dpp v251, v254, v254 row_mirror row_mask:0xf bank_mask:0xf bound_ctrl:1
	v_add_f32_dpp v251, v255, v255 row_mirror row_mask:0xf bank_mask:0xc bound_ctrl:1
	v_add_f32_dpp v250, v250, v250 row_half_mirror row_mask:0xf bank_mask:0xf bound_ctrl:1
	s_nop 0
	v_add_f32_dpp v250, v251, v251 row_half_mirror row_mask:0xf bank_mask:0xa bound_ctrl:1
	s_nop 1
	v_add_f32_dpp v250, v250, v250 quad_perm:[1, 0, 3, 2] row_mask:0xf bank_mask:0xf bound_ctrl:1
	s_nop 1
	v_add_f32_dpp v250, v250, v250 quad_perm:[2, 3, 0, 1] row_mask:0xf bank_mask:0xf bound_ctrl:1
	s_nop 0
	v_readlane_b32 s2, v250, 20
	v_readlane_b32 s10, v250, 52
	v_readlane_b32 s0, v250, 4
	v_readlane_b32 s1, v250, 36
	v_mov_b32_e32 v16, s2
	v_mov_b32_e32 v17, s10
	v_readlane_b32 s2, v250, 16
	v_readlane_b32 s10, v250, 48
	v_pk_add_f32 v[16:17], s[0:1], v[16:17]
	v_readlane_b32 s0, v250, 0
	v_readlane_b32 s1, v250, 32
	v_mov_b32_e32 v18, s2
	v_mov_b32_e32 v19, s10
	v_readlane_b32 s2, v250, 24
	v_readlane_b32 s10, v250, 56
	v_pk_add_f32 v[18:19], s[0:1], v[18:19]
	v_readlane_b32 s0, v250, 8
	v_readlane_b32 s1, v250, 40
	v_mov_b32_e32 v20, s2
	v_mov_b32_e32 v21, s10
	v_pk_add_f32 v[20:21], s[0:1], v[20:21]
	v_mov_b32_e32 v25, v18
	v_add_f32_e32 v26, v20, v21
	v_mov_b32_e32 v18, v17
	v_readlane_b32 s2, v250, 28
	v_readlane_b32 s10, v250, 60
	v_readlane_b32 s0, v250, 12
	v_readlane_b32 s1, v250, 44
	v_mov_b32_e32 v20, s2
	v_mov_b32_e32 v21, s10
	v_pk_add_f32 v[20:21], s[0:1], v[20:21]
	v_add_f32_e32 v27, v20, v21
	v_mov_b32_e32 v24, v16
	v_pk_add_f32 v[16:17], v[24:25], v[18:19]
	v_mov_b32_e32 v20, v178
	v_mov_b32_e32 v21, v179
	v_mov_b32_e32 v22, v180
	v_mov_b32_e32 v23, v181
	v_add_f32_e32 v19, v26, v22
	v_pk_add_f32 v[16:17], v[16:17], v[20:21]
	v_add_f32_e32 v18, v27, v23
	v_cmp_gt_f32_e32 vcc, v17, v16
	s_nop 0
	s_nop 0
	v_cndmask_b32_e32 v20, v16, v17, vcc
	v_cmp_gt_f32_e64 s[12:13], v19, v20
	v_cndmask_b32_e64 v21, 0, 1, vcc
	s_and_b64 s[10:11], s[12:13], exec
	v_cndmask_b32_e64 v20, v20, v19, s[12:13]
	v_cmp_ngt_f32_e64 s[0:1], v18, v20
	v_readfirstlane_b32 s2, v21
	s_cselect_b32 s2, 2, s2
	s_and_b64 s[10:11], s[0:1], exec
	s_cselect_b32 s2, s2, 3
	s_cmp_eq_u32 s2, 0
	s_waitcnt lgkmcnt(0)
	s_cbranch_scc0 .Lmy_rselb_1
	ds_read_b128 v[146:149], v60
	ds_read_b128 v[150:153], v60 offset:4096
	ds_read_b128 v[154:157], v60 offset:8192
	ds_read_b128 v[66:69], v60 offset:12288
	ds_read_b128 v[130:133], v60 offset:1024
	ds_read_b128 v[134:137], v60 offset:5120
	ds_read_b128 v[138:141], v60 offset:9216
	ds_read_b128 v[142:145], v60 offset:13312
	s_waitcnt lgkmcnt(7)
	v_mul_f32_e32 v252, v106, v146
	v_fmac_f32_e32 v252, v107, v147
	v_fmac_f32_e32 v252, v104, v148
	v_fmac_f32_e32 v252, v105, v149
	s_waitcnt lgkmcnt(6)
	v_mul_f32_e32 v253, v106, v150
	v_fmac_f32_e32 v253, v107, v151
	v_fmac_f32_e32 v253, v104, v152
	v_fmac_f32_e32 v253, v105, v153
	s_waitcnt lgkmcnt(5)
	v_mul_f32_e32 v254, v106, v154
	v_fmac_f32_e32 v254, v107, v155
	v_fmac_f32_e32 v254, v104, v156
	v_fmac_f32_e32 v254, v105, v157
	s_waitcnt lgkmcnt(4)
	v_mul_f32_e32 v255, v106, v66
	v_fmac_f32_e32 v255, v107, v67
	v_fmac_f32_e32 v255, v104, v68
	v_fmac_f32_e32 v255, v105, v69
	ds_read_b128 v[146:149], v60 offset:2048
	ds_read_b128 v[150:153], v60 offset:6144
	ds_read_b128 v[154:157], v60 offset:10240
	ds_read_b128 v[66:69], v60 offset:14336
	s_waitcnt lgkmcnt(7)
	v_fmac_f32_e32 v252, v108, v130
	v_fmac_f32_e32 v252, v109, v131
	v_fmac_f32_e32 v252, v110, v132
	v_fmac_f32_e32 v252, v111, v133
	s_waitcnt lgkmcnt(6)
	v_fmac_f32_e32 v253, v108, v134
	v_fmac_f32_e32 v253, v109, v135
	v_fmac_f32_e32 v253, v110, v136
	v_fmac_f32_e32 v253, v111, v137
	s_waitcnt lgkmcnt(5)
	v_fmac_f32_e32 v254, v108, v138
	v_fmac_f32_e32 v254, v109, v139
	v_fmac_f32_e32 v254, v110, v140
	v_fmac_f32_e32 v254, v111, v141
	s_waitcnt lgkmcnt(4)
	v_fmac_f32_e32 v255, v108, v142
	v_fmac_f32_e32 v255, v109, v143
	v_fmac_f32_e32 v255, v110, v144
	v_fmac_f32_e32 v255, v111, v145
	ds_read_b128 v[130:133], v60 offset:3072
	ds_read_b128 v[134:137], v60 offset:7168
	ds_read_b128 v[138:141], v60 offset:11264
	ds_read_b128 v[142:145], v60 offset:15360
	s_waitcnt lgkmcnt(7)
	v_fmac_f32_e32 v252, v50, v148
	v_fmac_f32_e32 v252, v51, v149
	v_fmac_f32_e32 v252, v48, v146
	v_fmac_f32_e32 v252, v49, v147
	s_waitcnt lgkmcnt(6)
	v_fmac_f32_e32 v253, v50, v152
	v_fmac_f32_e32 v253, v51, v153
	v_fmac_f32_e32 v253, v48, v150
	v_fmac_f32_e32 v253, v49, v151
	s_waitcnt lgkmcnt(5)
	v_fmac_f32_e32 v254, v50, v156
	v_fmac_f32_e32 v254, v51, v157
	v_fmac_f32_e32 v254, v48, v154
	v_fmac_f32_e32 v254, v49, v155
	s_waitcnt lgkmcnt(4)
	v_fmac_f32_e32 v255, v50, v68
	v_fmac_f32_e32 v255, v51, v69
	v_fmac_f32_e32 v255, v48, v66
	v_fmac_f32_e32 v255, v49, v67
	s_waitcnt lgkmcnt(3)
	v_fmac_f32_e32 v252, v52, v130
	v_fmac_f32_e32 v252, v53, v131
	v_fmac_f32_e32 v252, v54, v132
	v_fmac_f32_e32 v252, v55, v133
	s_waitcnt lgkmcnt(2)
	v_fmac_f32_e32 v253, v52, v134
	v_fmac_f32_e32 v253, v53, v135
	v_fmac_f32_e32 v253, v54, v136
	v_fmac_f32_e32 v253, v55, v137
	s_waitcnt lgkmcnt(1)
	v_fmac_f32_e32 v254, v52, v138
	v_fmac_f32_e32 v254, v53, v139
	v_fmac_f32_e32 v254, v54, v140
	v_fmac_f32_e32 v254, v55, v141
	s_waitcnt lgkmcnt(0)
	v_fmac_f32_e32 v255, v52, v142
	v_fmac_f32_e32 v255, v53, v143
	v_fmac_f32_e32 v255, v54, v144
	v_fmac_f32_e32 v255, v55, v145
	v_add_f32_dpp v94, v252, v252 row_mirror row_mask:0xf bank_mask:0xf bound_ctrl:1
	v_add_f32_dpp v94, v253, v253 row_mirror row_mask:0xf bank_mask:0xc bound_ctrl:1
	v_add_f32_dpp v96, v254, v254 row_mirror row_mask:0xf bank_mask:0xf bound_ctrl:1
	v_add_f32_dpp v96, v255, v255 row_mirror row_mask:0xf bank_mask:0xc bound_ctrl:1
	v_add_f32_dpp v94, v94, v94 row_half_mirror row_mask:0xf bank_mask:0xf bound_ctrl:1
	s_nop 0
	v_add_f32_dpp v94, v96, v96 row_half_mirror row_mask:0xf bank_mask:0xa bound_ctrl:1
	s_nop 1
	v_add_f32_dpp v94, v94, v94 quad_perm:[1,0,3,2] row_mask:0xf bank_mask:0xf bound_ctrl:1
	s_nop 1
	v_add_f32_dpp v94, v94, v94 quad_perm:[2,3,0,1] row_mask:0xf bank_mask:0xf bound_ctrl:1
	s_nop 0
	v_readlane_b32 s14, v94, 0
	v_readlane_b32 s94, v94, 16
	v_readlane_b32 s15, v94, 32
	v_readlane_b32 s95, v94, 48
	v_readlane_b32 s87, v94, 8
	v_readlane_b32 s91, v94, 24
	v_readlane_b32 s90, v94, 40
	v_readlane_b32 s92, v94, 56
	v_readlane_b32 s65, v94, 4
	v_readlane_b32 s75, v94, 20
	v_readlane_b32 s66, v94, 36
	v_readlane_b32 s78, v94, 52
	v_readlane_b32 s51, v94, 12
	v_readlane_b32 s53, v94, 28
	v_readlane_b32 s52, v94, 44
	v_readlane_b32 s54, v94, 60
	s_branch .Lmy_rselb_end
